# v24 + attention epilogues (FoX, MLA, stick-breaking): the 8 serialized SiLU-gate loads issued together into fresh registers, one wait
# baseline (speedup 1.0000x reference)
; DI u32x2 pack4(float a, float b, float c, float d) { u32x2 r; r.x = pack2(a, b); r.y = pack2(c, d); return r; }
; template <int DK, int MODE> ...
;     ...
;   float inv = 1.f;
;   if (MODE != 2) { const float lt = lsum + __shfl_xor(lsum, 32); inv = 1.f / lt; }
;   const bf16_t* gp = gate + (size_t)qpos * 1024;
;   bf16_t* op = outp + (size_t)qpos * 1024;
; #pragma unroll
;   for (int dt = 0; dt < 2; ++dt)
; #pragma unroll
;     for (int g = 0; g < 4; ++g) {
;       const int dv = 32 * dt + 8 * g + 4 * h;
;       const u32x2 gv = *(const u32x2*)(gp + dv);
;       const f32x16& o = dt ? o1 : o0;
;       const float g0 = __uint_as_float(gv.x << 16), g1 = __uint_as_float(gv.x & 0xffff0000u), g2 = __uint_as_float(gv.y << 16), g3 = __uint_as_float(gv.y & 0xffff0000u);
;       *(u32x2*)(op + dv) = pack4(o[4 * g] * inv * g0, o[4 * g + 1] * inv * g1, o[4 * g + 2] * inv * g2, o[4 * g + 3] * inv * g3);
;     }
.LBB0_520:
	s_lshl_b32 s2, s17, 1
	s_add_u32 s0, s6, s2
	ds_bpermute_b32 v0, v151, v135
	s_addc_u32 s1, s7, 0
	s_lshl_b32 s6, s65, 1
	s_add_u32 s0, s0, s6
	s_addc_u32 s1, s1, 0
	s_add_u32 s2, s4, s2
	s_addc_u32 s5, s5, 0
	s_waitcnt lgkmcnt(0)
	v_add_f32_e32 v0, v135, v0
	s_add_u32 s4, s2, s6
	v_div_scale_f32 v36, s[6:7], v0, v0, 1.0
	v_rcp_f32_e32 v37, v36
	v_mov_b32_e32 v35, v1
	s_addc_u32 s5, s5, 0
	v_fma_f32 v38, -v36, v37, 1.0
	v_fmac_f32_e32 v37, v38, v37
	v_div_scale_f32 v38, vcc, 1.0, v0, 1.0
	v_mul_f32_e32 v39, v38, v37
	v_fma_f32 v40, -v36, v39, v38
	v_fmac_f32_e32 v39, v40, v37
	v_fma_f32 v36, -v36, v39, v38
	v_div_fmas_f32 v36, v36, v37, v39
	v_div_fixup_f32 v0, v36, v0, 1.0
	v_lshlrev_b64 v[36:37], 11, v[130:131]
	v_lshl_add_u64 v[38:39], s[0:1], 0, v[36:37]
	v_lshlrev_b64 v[40:41], 1, v[34:35]
	v_lshl_add_u64 v[34:35], v[38:39], 0, v[40:41]
	global_load_dwordx2 v[224:225], v[34:35], off
	global_load_dwordx2 v[226:227], v[34:35], off offset:16
	global_load_dwordx2 v[228:229], v[34:35], off offset:32
	global_load_dwordx2 v[230:231], v[34:35], off offset:48
	global_load_dwordx2 v[232:233], v[34:35], off offset:64
	global_load_dwordx2 v[234:235], v[34:35], off offset:80
	global_load_dwordx2 v[236:237], v[34:35], off offset:96
	global_load_dwordx2 v[238:239], v[34:35], off offset:112
	v_pk_mul_f32 v[20:21], v[20:21], v[0:1] op_sel_hi:[1,0]
	v_pk_mul_f32 v[18:19], v[18:19], v[0:1] op_sel_hi:[1,0]
	v_lshl_add_u64 v[36:37], s[4:5], 0, v[36:37]
	v_pk_mul_f32 v[22:23], v[22:23], v[0:1] op_sel_hi:[1,0]
	v_pk_mul_f32 v[24:25], v[24:25], v[0:1] op_sel_hi:[1,0]
	v_pk_mul_f32 v[2:3], v[2:3], v[0:1] op_sel_hi:[1,0]
	v_pk_mul_f32 v[4:5], v[4:5], v[0:1] op_sel_hi:[1,0]
	v_pk_mul_f32 v[6:7], v[6:7], v[0:1] op_sel_hi:[1,0]
	s_waitcnt vmcnt(0)
	v_lshlrev_b32_e32 v42, 16, v224
	v_and_b32_e32 v43, 0xffff0000, v224
	v_lshlrev_b32_e32 v38, 16, v225
	v_and_b32_e32 v39, 0xffff0000, v225
	v_pk_mul_f32 v[20:21], v[20:21], v[38:39]
	v_pk_mul_f32 v[18:19], v[18:19], v[42:43]
	v_cvt_pk_bf16_f32 v39, v20, v21
	v_cvt_pk_bf16_f32 v38, v18, v19
	v_lshl_add_u64 v[18:19], v[36:37], 0, v[40:41]
	global_store_dwordx2 v[18:19], v[38:39], off
	v_lshlrev_b32_e32 v36, 16, v226
	v_and_b32_e32 v37, 0xffff0000, v226
	v_lshlrev_b32_e32 v20, 16, v227
	v_and_b32_e32 v21, 0xffff0000, v227
	v_pk_mul_f32 v[22:23], v[22:23], v[36:37]
	v_pk_mul_f32 v[20:21], v[24:25], v[20:21]
	v_cvt_pk_bf16_f32 v22, v22, v23
	v_cvt_pk_bf16_f32 v23, v20, v21
	v_pk_mul_f32 v[24:25], v[26:27], v[0:1] op_sel_hi:[1,0]
	global_store_dwordx2 v[18:19], v[22:23], off offset:16
	v_lshlrev_b32_e32 v22, 16, v228
	v_and_b32_e32 v23, 0xffff0000, v228
	v_pk_mul_f32 v[22:23], v[24:25], v[22:23]
	v_lshlrev_b32_e32 v20, 16, v229
	v_and_b32_e32 v21, 0xffff0000, v229
	v_pk_mul_f32 v[24:25], v[28:29], v[0:1] op_sel_hi:[1,0]
	v_cvt_pk_bf16_f32 v22, v22, v23
	v_pk_mul_f32 v[20:21], v[24:25], v[20:21]
	v_pk_mul_f32 v[24:25], v[30:31], v[0:1] op_sel_hi:[1,0]
	v_cvt_pk_bf16_f32 v23, v20, v21
	s_nop 0
	global_store_dwordx2 v[18:19], v[22:23], off offset:32
	v_lshlrev_b32_e32 v22, 16, v230
	v_and_b32_e32 v23, 0xffff0000, v230
	v_pk_mul_f32 v[22:23], v[24:25], v[22:23]
	v_lshlrev_b32_e32 v20, 16, v231
	v_and_b32_e32 v21, 0xffff0000, v231
	v_pk_mul_f32 v[24:25], v[32:33], v[0:1] op_sel_hi:[1,0]
	v_cvt_pk_bf16_f32 v22, v22, v23
	v_pk_mul_f32 v[20:21], v[24:25], v[20:21]
	s_nop 0
	v_cvt_pk_bf16_f32 v23, v20, v21
	s_nop 0
	global_store_dwordx2 v[18:19], v[22:23], off offset:48
	v_lshlrev_b32_e32 v22, 16, v232
	v_and_b32_e32 v23, 0xffff0000, v232
	v_lshlrev_b32_e32 v20, 16, v233
	v_and_b32_e32 v21, 0xffff0000, v233
	v_pk_mul_f32 v[2:3], v[2:3], v[22:23]
	v_pk_mul_f32 v[4:5], v[4:5], v[20:21]
	v_cvt_pk_bf16_f32 v2, v2, v3
	v_cvt_pk_bf16_f32 v3, v4, v5
	global_store_dwordx2 v[18:19], v[2:3], off offset:64
	v_lshlrev_b32_e32 v4, 16, v234
	v_and_b32_e32 v5, 0xffff0000, v234
	v_pk_mul_f32 v[4:5], v[6:7], v[4:5]
	v_lshlrev_b32_e32 v2, 16, v235
	v_and_b32_e32 v3, 0xffff0000, v235
	v_pk_mul_f32 v[6:7], v[8:9], v[0:1] op_sel_hi:[1,0]
	v_cvt_pk_bf16_f32 v4, v4, v5
	v_pk_mul_f32 v[2:3], v[6:7], v[2:3]
	v_pk_mul_f32 v[6:7], v[10:11], v[0:1] op_sel_hi:[1,0]
	v_cvt_pk_bf16_f32 v5, v2, v3
	s_nop 0
	global_store_dwordx2 v[18:19], v[4:5], off offset:80
	v_lshlrev_b32_e32 v4, 16, v236
	v_and_b32_e32 v5, 0xffff0000, v236
	v_pk_mul_f32 v[4:5], v[6:7], v[4:5]
	v_lshlrev_b32_e32 v2, 16, v237
	v_and_b32_e32 v3, 0xffff0000, v237
	v_pk_mul_f32 v[6:7], v[12:13], v[0:1] op_sel_hi:[1,0]
	v_cvt_pk_bf16_f32 v4, v4, v5
	v_pk_mul_f32 v[2:3], v[6:7], v[2:3]
	v_pk_mul_f32 v[6:7], v[14:15], v[0:1] op_sel_hi:[1,0]
	v_cvt_pk_bf16_f32 v5, v2, v3
	s_nop 0
	global_store_dwordx2 v[18:19], v[4:5], off offset:96
	v_lshlrev_b32_e32 v4, 16, v238
	v_and_b32_e32 v5, 0xffff0000, v238
	v_pk_mul_f32 v[4:5], v[6:7], v[4:5]
	v_lshlrev_b32_e32 v2, 16, v239
	v_and_b32_e32 v3, 0xffff0000, v239
	v_pk_mul_f32 v[6:7], v[16:17], v[0:1] op_sel_hi:[1,0]
	v_cvt_pk_bf16_f32 v4, v4, v5
	v_pk_mul_f32 v[2:3], v[6:7], v[2:3]
	s_nop 0
	v_cvt_pk_bf16_f32 v5, v2, v3
	global_store_dwordx2 v[18:19], v[4:5], off offset:112
	s_barrier

; DI u32x2 pack4(float a, float b, float c, float d) { u32x2 r; r.x = pack2(a, b); r.y = pack2(c, d); return r; }
; template <int DK, int MODE> ...
;     ...
;   float inv = 1.f;
;   if (MODE != 2) { const float lt = lsum + __shfl_xor(lsum, 32); inv = 1.f / lt; }
;   const bf16_t* gp = gate + (size_t)qpos * 1024;
;   bf16_t* op = outp + (size_t)qpos * 1024;
; #pragma unroll
;   for (int dt = 0; dt < 2; ++dt)
; #pragma unroll
;     for (int g = 0; g < 4; ++g) {
;       const int dv = 32 * dt + 8 * g + 4 * h;
;       const u32x2 gv = *(const u32x2*)(gp + dv);
;       const f32x16& o = dt ? o1 : o0;
;       const float g0 = __uint_as_float(gv.x << 16), g1 = __uint_as_float(gv.x & 0xffff0000u), g2 = __uint_as_float(gv.y << 16), g3 = __uint_as_float(gv.y & 0xffff0000u);
;       *(u32x2*)(op + dv) = pack4(o[4 * g] * inv * g0, o[4 * g + 1] * inv * g1, o[4 * g + 2] * inv * g2, o[4 * g + 3] * inv * g3);
;     }
.LBB0_540:
	s_lshl_b32 s1, s17, 1
	s_add_u32 s2, s6, s1
	s_addc_u32 s6, s7, 0
	s_add_u32 s1, s4, s1
	s_addc_u32 s7, s5, 0
	s_lshl_b32 s8, s65, 1
	s_add_u32 s4, s2, s8
	s_addc_u32 s5, s6, 0
	s_add_u32 s6, s1, s8
	s_addc_u32 s7, s7, 0
	v_cmp_lt_i32_e32 vcc, v0, v15
	s_barrier
	s_nop 0
	v_cndmask_b32_e32 v0, v14, v0, vcc
	v_lshlrev_b32_e32 v0, 2, v0
	ds_bpermute_b32 v0, v0, v6
	s_waitcnt lgkmcnt(0)
	v_add_f32_e32 v0, v6, v0
	v_div_scale_f32 v2, s[8:9], v0, v0, 1.0
	v_rcp_f32_e32 v3, v2
	s_nop 0
	v_fma_f32 v4, -v2, v3, 1.0
	v_fmac_f32_e32 v3, v4, v3
	v_div_scale_f32 v4, vcc, 1.0, v0, 1.0
	v_mul_f32_e32 v5, v4, v3
	v_fma_f32 v6, -v2, v5, v4
	v_fmac_f32_e32 v5, v6, v3
	v_fma_f32 v2, -v2, v5, v4
	v_div_fmas_f32 v2, v2, v3, v5
	v_lshlrev_b64 v[4:5], 11, v[152:153]
	v_div_fixup_f32 v2, v2, v0, 1.0
	v_lshl_add_u64 v[6:7], s[4:5], 0, v[4:5]
	v_lshlrev_b32_e32 v0, 1, v149
	v_lshl_add_u64 v[6:7], v[6:7], 0, v[0:1]
	global_load_dwordx2 v[224:225], v[6:7], off offset:1024
	global_load_dwordx2 v[226:227], v[6:7], off offset:1040
	global_load_dwordx2 v[228:229], v[6:7], off offset:1056
	global_load_dwordx2 v[230:231], v[6:7], off offset:1072
	global_load_dwordx2 v[232:233], v[6:7], off offset:1088
	global_load_dwordx2 v[234:235], v[6:7], off offset:1104
	global_load_dwordx2 v[236:237], v[6:7], off offset:1120
	global_load_dwordx2 v[238:239], v[6:7], off offset:1136
	v_pk_mul_f32 v[12:13], v[64:65], v[2:3] op_sel_hi:[1,0]
	v_lshl_add_u64 v[4:5], s[6:7], 0, v[4:5]
	v_lshl_add_u64 v[4:5], v[4:5], 0, v[0:1]
	s_mov_b64 s[4:5], 0
	s_waitcnt vmcnt(0)
	v_lshlrev_b32_e32 v10, 16, v224
	v_and_b32_e32 v11, 0xffff0000, v224
	v_pk_mul_f32 v[10:11], v[12:13], v[10:11]
	v_lshlrev_b32_e32 v8, 16, v225
	v_and_b32_e32 v9, 0xffff0000, v225
	v_pk_mul_f32 v[12:13], v[66:67], v[2:3] op_sel_hi:[1,0]
	v_cvt_pk_bf16_f32 v10, v10, v11
	v_pk_mul_f32 v[8:9], v[12:13], v[8:9]
	v_pk_mul_f32 v[12:13], v[68:69], v[2:3] op_sel_hi:[1,0]
	v_cvt_pk_bf16_f32 v11, v8, v9
	s_nop 0
	global_store_dwordx2 v[4:5], v[10:11], off offset:1024
	v_lshlrev_b32_e32 v10, 16, v226
	v_and_b32_e32 v11, 0xffff0000, v226
	v_pk_mul_f32 v[10:11], v[12:13], v[10:11]
	v_lshlrev_b32_e32 v8, 16, v227
	v_and_b32_e32 v9, 0xffff0000, v227
	v_pk_mul_f32 v[12:13], v[70:71], v[2:3] op_sel_hi:[1,0]
	v_cvt_pk_bf16_f32 v10, v10, v11
	v_pk_mul_f32 v[8:9], v[12:13], v[8:9]
	v_pk_mul_f32 v[12:13], v[72:73], v[2:3] op_sel_hi:[1,0]
	v_cvt_pk_bf16_f32 v11, v8, v9
	s_nop 0
	global_store_dwordx2 v[4:5], v[10:11], off offset:1040
	v_lshlrev_b32_e32 v10, 16, v228
	v_and_b32_e32 v11, 0xffff0000, v228
	v_pk_mul_f32 v[10:11], v[12:13], v[10:11]
	v_lshlrev_b32_e32 v8, 16, v229
	v_and_b32_e32 v9, 0xffff0000, v229
	v_pk_mul_f32 v[12:13], v[74:75], v[2:3] op_sel_hi:[1,0]
	v_cvt_pk_bf16_f32 v10, v10, v11
	v_pk_mul_f32 v[8:9], v[12:13], v[8:9]
	v_pk_mul_f32 v[12:13], v[76:77], v[2:3] op_sel_hi:[1,0]
	v_cvt_pk_bf16_f32 v11, v8, v9
	s_nop 0
	global_store_dwordx2 v[4:5], v[10:11], off offset:1056
	v_lshlrev_b32_e32 v10, 16, v230
	v_and_b32_e32 v11, 0xffff0000, v230
	v_pk_mul_f32 v[10:11], v[12:13], v[10:11]
	v_lshlrev_b32_e32 v8, 16, v231
	v_and_b32_e32 v9, 0xffff0000, v231
	v_pk_mul_f32 v[12:13], v[78:79], v[2:3] op_sel_hi:[1,0]
	v_cvt_pk_bf16_f32 v10, v10, v11
	v_pk_mul_f32 v[8:9], v[12:13], v[8:9]
	v_pk_mul_f32 v[12:13], v[48:49], v[2:3] op_sel_hi:[1,0]
	v_cvt_pk_bf16_f32 v11, v8, v9
	s_nop 0
	global_store_dwordx2 v[4:5], v[10:11], off offset:1072
	v_lshlrev_b32_e32 v10, 16, v232
	v_and_b32_e32 v11, 0xffff0000, v232
	v_pk_mul_f32 v[10:11], v[12:13], v[10:11]
	v_lshlrev_b32_e32 v8, 16, v233
	v_and_b32_e32 v9, 0xffff0000, v233
	v_pk_mul_f32 v[12:13], v[50:51], v[2:3] op_sel_hi:[1,0]
	v_cvt_pk_bf16_f32 v10, v10, v11
	v_pk_mul_f32 v[8:9], v[12:13], v[8:9]
	v_pk_mul_f32 v[12:13], v[52:53], v[2:3] op_sel_hi:[1,0]
	v_cvt_pk_bf16_f32 v11, v8, v9
	s_nop 0
	global_store_dwordx2 v[4:5], v[10:11], off offset:1088
	v_lshlrev_b32_e32 v10, 16, v234
	v_and_b32_e32 v11, 0xffff0000, v234
	v_pk_mul_f32 v[10:11], v[12:13], v[10:11]
	v_lshlrev_b32_e32 v8, 16, v235
	v_and_b32_e32 v9, 0xffff0000, v235
	v_pk_mul_f32 v[12:13], v[54:55], v[2:3] op_sel_hi:[1,0]
	v_cvt_pk_bf16_f32 v10, v10, v11
	v_pk_mul_f32 v[8:9], v[12:13], v[8:9]
	v_pk_mul_f32 v[12:13], v[56:57], v[2:3] op_sel_hi:[1,0]
	v_cvt_pk_bf16_f32 v11, v8, v9
	s_nop 0
	s_nop 0
	global_store_dwordx2 v[4:5], v[10:11], off offset:1104
	v_lshlrev_b32_e32 v10, 16, v236
	v_and_b32_e32 v11, 0xffff0000, v236
	v_pk_mul_f32 v[10:11], v[12:13], v[10:11]
	v_lshlrev_b32_e32 v8, 16, v237
	v_and_b32_e32 v9, 0xffff0000, v237
	v_pk_mul_f32 v[12:13], v[58:59], v[2:3] op_sel_hi:[1,0]
	v_cvt_pk_bf16_f32 v10, v10, v11
	v_pk_mul_f32 v[8:9], v[12:13], v[8:9]
	s_nop 0
	v_cvt_pk_bf16_f32 v11, v8, v9
	global_store_dwordx2 v[4:5], v[10:11], off offset:1120
	v_lshlrev_b32_e32 v8, 16, v238
	v_and_b32_e32 v9, 0xffff0000, v238
	v_pk_mul_f32 v[10:11], v[60:61], v[2:3] op_sel_hi:[1,0]
	v_lshlrev_b32_e32 v6, 16, v239
	v_and_b32_e32 v7, 0xffff0000, v239
	v_pk_mul_f32 v[2:3], v[62:63], v[2:3] op_sel_hi:[1,0]
	v_pk_mul_f32 v[8:9], v[10:11], v[8:9]
	v_pk_mul_f32 v[2:3], v[2:3], v[6:7]
	v_cvt_pk_bf16_f32 v6, v8, v9
	v_cvt_pk_bf16_f32 v7, v2, v3
	global_store_dwordx2 v[4:5], v[6:7], off offset:1136
	s_barrier

; DI int get_tid() { int t = threadIdx.x; asm volatile("" : "+v"(t)); return t; }
; DI u32x2 pack4(float a, float b, float c, float d) { u32x2 r; r.x = pack2(a, b); r.y = pack2(c, d); return r; }
; template <int DK, int MODE> ...
;     ...
;   const int tid = get_tid(), lane = tid & 63, wave = __builtin_amdgcn_readfirstlane(tid >> 6), l32 = lane & 31, h = lane >> 5;
;   const int tq0 = qb * 128 + 32 * wave;
;   const int qpos = tq0 + l32;
;   bf16x8 qf[NKS];
;   {
;     const bf16_t* qp = Q + (size_t)qpos * DK + h * 8;
; #pragma unroll
;     for (int ks = 0; ks < NKS; ++ks) qf[ks] = *(const bf16x8*)(qp + ks * 16);
; #pragma unroll
;     for (int ks = 0; ks < NKS; ++ks) asm volatile("" : "+v"(qf[ks]));
;   }
;   float Fref = 0.f;
;   if (MODE == 1) Fref = F[qb * 128];
;   f32x16 o0, o1;
; #pragma unroll
;   for (int e = 0; e < 16; ++e) { o0[e] = 0.f; o1[e] = 0.f; }
;   float m = -1e30f, lsum = 0.f, R = 1.f;
;   u32x4 rk[NKL], rv[2];
;   float rf = 0.f;
;   auto gload = [&](int jt) {
; #pragma unroll
;     for (int i = 0; i < NKL; ++i) {
;       const int id = tid + 256 * i, row = id / KCH, ch = id % KCH;
;       rk[i] = *(const u32x4*)(K + (size_t)(jt * 64 + row) * DK + ch * 8);
;     }
; #pragma unroll
;     for (int i = 0; i < 2; ++i) {
;       const int id = tid + 256 * i, row = id >> 3, ch = id & 7;
;       rv[i] = *(const u32x4*)(Vt + (size_t)row * Skv + jt * 64 + ch * 8);
;     }
;     if (MODE == 1) rf = F[jt * 64 + (tid & 63)];
;   };
;     ...
;   const bf16_t* gp = gate + (size_t)qpos * 1024;
;   bf16_t* op = outp + (size_t)qpos * 1024;
; #pragma unroll
;   for (int dt = 0; dt < 2; ++dt)
; #pragma unroll
;     for (int g = 0; g < 4; ++g) {
;       const int dv = 32 * dt + 8 * g + 4 * h;
;       const u32x2 gv = *(const u32x2*)(gp + dv);
;       const f32x16& o = dt ? o1 : o0;
;       const float g0 = __uint_as_float(gv.x << 16), g1 = __uint_as_float(gv.x & 0xffff0000u), g2 = __uint_as_float(gv.y << 16), g3 = __uint_as_float(gv.y & 0xffff0000u);
;       *(u32x2*)(op + dv) = pack4(o[4 * g] * inv * g0, o[4 * g + 1] * inv * g1, o[4 * g + 2] * inv * g2, o[4 * g + 3] * inv * g3);
;     }
.LBB0_588:
	s_lshl_b32 s2, s28, 7
	s_and_b32 s2, s2, 0x180
	s_add_u32 s6, s11, s2
	v_readlane_b32 s4, v214, 5
	s_addc_u32 s7, s4, 0
	v_lshlrev_b64 v[2:3], 11, v[132:133]
	v_lshl_add_u64 v[4:5], s[6:7], 0, v[2:3]
	v_lshlrev_b32_e32 v0, 1, v135
	v_lshl_add_u64 v[4:5], v[4:5], 0, v[0:1]
	global_load_dwordx2 v[224:225], v[4:5], off offset:512
	global_load_dwordx2 v[226:227], v[4:5], off offset:528
	global_load_dwordx2 v[228:229], v[4:5], off offset:544
	global_load_dwordx2 v[230:231], v[4:5], off offset:560
	global_load_dwordx2 v[232:233], v[4:5], off offset:576
	global_load_dwordx2 v[234:235], v[4:5], off offset:592
	global_load_dwordx2 v[236:237], v[4:5], off offset:608
	global_load_dwordx2 v[238:239], v[4:5], off offset:624
	v_readlane_b32 s4, v214, 6
	s_add_u32 s4, s4, s2
	v_readlane_b32 s2, v214, 7
	s_addc_u32 s5, s2, 0
	v_lshl_add_u64 v[2:3], s[4:5], 0, v[2:3]
	v_lshl_add_u64 v[2:3], v[2:3], 0, v[0:1]
	s_lshl_b32 s2, s28, 14
	v_readlane_b32 s8, v214, 8
	s_add_i32 s2, s2, s8
	s_lshl_b32 s16, s20, 1
	s_movk_i32 s54, 0x90
	s_waitcnt vmcnt(0)
	v_lshlrev_b32_e32 v8, 16, v224
	v_and_b32_e32 v9, 0xffff0000, v224
	v_lshlrev_b32_e32 v6, 16, v225
	v_and_b32_e32 v7, 0xffff0000, v225
	v_pk_mul_f32 v[8:9], v[32:33], v[8:9]
	v_pk_mul_f32 v[6:7], v[34:35], v[6:7]
	v_cvt_pk_bf16_f32 v8, v8, v9
	v_cvt_pk_bf16_f32 v9, v6, v7
	s_nop 0
	global_store_dwordx2 v[2:3], v[8:9], off offset:512
	v_lshlrev_b32_e32 v8, 16, v226
	v_and_b32_e32 v9, 0xffff0000, v226
	v_lshlrev_b32_e32 v6, 16, v227
	v_and_b32_e32 v7, 0xffff0000, v227
	v_pk_mul_f32 v[8:9], v[36:37], v[8:9]
	v_pk_mul_f32 v[6:7], v[38:39], v[6:7]
	v_cvt_pk_bf16_f32 v8, v8, v9
	v_cvt_pk_bf16_f32 v9, v6, v7
	s_nop 0
	global_store_dwordx2 v[2:3], v[8:9], off offset:528
	v_lshlrev_b32_e32 v8, 16, v228
	v_and_b32_e32 v9, 0xffff0000, v228
	v_lshlrev_b32_e32 v6, 16, v229
	v_and_b32_e32 v7, 0xffff0000, v229
	v_pk_mul_f32 v[8:9], v[40:41], v[8:9]
	v_pk_mul_f32 v[6:7], v[42:43], v[6:7]
	v_cvt_pk_bf16_f32 v8, v8, v9
	v_cvt_pk_bf16_f32 v9, v6, v7
	s_nop 0
	global_store_dwordx2 v[2:3], v[8:9], off offset:544
	v_lshlrev_b32_e32 v8, 16, v230
	v_and_b32_e32 v9, 0xffff0000, v230
	v_lshlrev_b32_e32 v6, 16, v231
	v_and_b32_e32 v7, 0xffff0000, v231
	v_pk_mul_f32 v[8:9], v[44:45], v[8:9]
	v_pk_mul_f32 v[6:7], v[46:47], v[6:7]
	v_cvt_pk_bf16_f32 v8, v8, v9
	v_cvt_pk_bf16_f32 v9, v6, v7
	s_nop 0
	global_store_dwordx2 v[2:3], v[8:9], off offset:560
	v_lshlrev_b32_e32 v8, 16, v232
	v_and_b32_e32 v9, 0xffff0000, v232
	v_lshlrev_b32_e32 v6, 16, v233
	v_and_b32_e32 v7, 0xffff0000, v233
	v_pk_mul_f32 v[8:9], v[16:17], v[8:9]
	v_pk_mul_f32 v[6:7], v[18:19], v[6:7]
	v_cvt_pk_bf16_f32 v8, v8, v9
	v_cvt_pk_bf16_f32 v9, v6, v7
	s_nop 0
	global_store_dwordx2 v[2:3], v[8:9], off offset:576
	v_lshlrev_b32_e32 v8, 16, v234
	v_and_b32_e32 v9, 0xffff0000, v234
	v_lshlrev_b32_e32 v6, 16, v235
	v_and_b32_e32 v7, 0xffff0000, v235
	v_pk_mul_f32 v[8:9], v[20:21], v[8:9]
	v_pk_mul_f32 v[6:7], v[22:23], v[6:7]
	v_cvt_pk_bf16_f32 v8, v8, v9
	v_cvt_pk_bf16_f32 v9, v6, v7
	s_nop 0
	s_nop 0
	global_store_dwordx2 v[2:3], v[8:9], off offset:592
	v_lshlrev_b32_e32 v8, 16, v236
	v_and_b32_e32 v9, 0xffff0000, v236
	v_lshlrev_b32_e32 v6, 16, v237
	v_and_b32_e32 v7, 0xffff0000, v237
	v_pk_mul_f32 v[8:9], v[24:25], v[8:9]
	v_pk_mul_f32 v[6:7], v[26:27], v[6:7]
	v_cvt_pk_bf16_f32 v8, v8, v9
	v_cvt_pk_bf16_f32 v9, v6, v7
	v_lshlrev_b32_e32 v6, 16, v238
	v_and_b32_e32 v7, 0xffff0000, v238
	v_lshlrev_b32_e32 v4, 16, v239
	v_and_b32_e32 v5, 0xffff0000, v239
	v_pk_mul_f32 v[6:7], v[28:29], v[6:7]
	v_pk_mul_f32 v[4:5], v[30:31], v[4:5]
	v_cvt_pk_bf16_f32 v6, v6, v7
	v_cvt_pk_bf16_f32 v7, v4, v5
	global_store_dwordx2 v[2:3], v[8:9], off offset:608
	global_store_dwordx2 v[2:3], v[6:7], off offset:624
	s_barrier
	s_load_dwordx4 s[40:43], s[18:19], 0x118
	s_load_dwordx2 s[12:13], s[18:19], 0x128
	v_mov_b32_e32 v28, v188
	s_waitcnt lgkmcnt(0)
	s_add_u32 s28, s40, s16
	s_addc_u32 s29, s41, 0
	s_lshl_b32 s2, s2, 1
	s_add_u32 s22, s42, s2
	s_addc_u32 s23, s43, 0
	s_add_u32 s24, s12, s2
	v_readfirstlane_b32 s2, v28
	s_addc_u32 s25, s13, 0
	s_ashr_i32 s2, s2, 1
	s_andn2_b32 s2, s2, 31
	v_and_b32_e32 v36, 31, v28
	s_add_i32 s2, s2, s21
	v_or_b32_e32 v130, s2, v36
	v_ashrrev_i32_e32 v131, 31, v130
	v_bfe_u32 v149, v28, 5, 1
	v_lshlrev_b64 v[2:3], 7, v[130:131]
	v_lshl_add_u64 v[2:3], s[28:29], 0, v[2:3]
	v_lshlrev_b32_e32 v0, 4, v149
	v_lshl_add_u64 v[2:3], v[2:3], 0, v[0:1]
	global_load_dwordx4 v[78:81], v[2:3], off
	global_load_dwordx4 v[74:77], v[2:3], off offset:32
	global_load_dwordx4 v[70:73], v[2:3], off offset:64
	global_load_dwordx4 v[66:69], v[2:3], off offset:96
	v_ashrrev_i32_e32 v2, 31, v28
	v_lshrrev_b32_e32 v2, 29, v2
	v_add_u32_e32 v2, v28, v2
	v_ashrrev_i32_e32 v18, 3, v2
	v_ashrrev_i32_e32 v19, 31, v18
	v_lshlrev_b64 v[10:11], 7, v[18:19]
	v_add_u32_e32 v19, 0x100, v28
	v_ashrrev_i32_e32 v6, 31, v19
	v_and_b32_e32 v2, -8, v2
	v_lshrrev_b32_e32 v6, 29, v6
	v_sub_u32_e32 v37, v28, v2
	v_add_u32_e32 v6, v19, v6
	v_lshlrev_b32_e32 v4, 3, v37
	v_ashrrev_i32_e32 v24, 3, v6
	v_and_b32_e32 v6, -8, v6
	v_ashrrev_i32_e32 v5, 31, v4
	v_sub_u32_e32 v38, v19, v6
	v_lshl_add_u64 v[2:3], s[22:23], 0, v[10:11]
	v_lshlrev_b64 v[14:15], 1, v[4:5]
	v_ashrrev_i32_e32 v25, 31, v24
	v_lshlrev_b32_e32 v8, 3, v38
	v_lshl_add_u64 v[2:3], v[2:3], 0, v[14:15]
	v_lshlrev_b64 v[12:13], 7, v[24:25]
	v_ashrrev_i32_e32 v9, 31, v8
	global_load_dwordx4 v[2:5], v[2:3], off
	v_lshl_add_u64 v[6:7], s[22:23], 0, v[12:13]
	v_lshlrev_b64 v[16:17], 1, v[8:9]
	v_lshl_add_u64 v[6:7], v[6:7], 0, v[16:17]
	global_load_dwordx4 v[6:9], v[6:7], off
	v_ashrrev_i32_e32 v20, 3, v28
	v_ashrrev_i32_e32 v34, 3, v19
	v_ashrrev_i32_e32 v21, 31, v20
	v_ashrrev_i32_e32 v35, 31, v34
	v_lshlrev_b64 v[22:23], 9, v[20:21]
	v_lshlrev_b32_e32 v21, 4, v28
	v_lshlrev_b64 v[30:31], 9, v[34:35]
	v_lshl_add_u64 v[26:27], s[24:25], 0, v[22:23]
	v_and_b32_e32 v22, 0x70, v21
	v_mov_b32_e32 v23, v1
	v_lshl_add_u64 v[30:31], s[24:25], 0, v[30:31]
	v_lshl_add_u64 v[136:137], v[26:27], 0, v[22:23]
	v_lshl_add_u64 v[138:139], v[30:31], 0, v[22:23]
	global_load_dwordx4 v[26:29], v[136:137], off
	global_load_dwordx4 v[30:33], v[138:139], off
	v_mul_lo_u32 v18, v18, s54
	v_lshl_add_u32 v151, v37, 4, v18
	s_movk_i32 s2, 0x2000
	v_mad_u64_u32 v[132:133], s[12:13], v20, s54, v[22:23]
	v_mad_u64_u32 v[134:135], s[12:13], v34, s54, v[22:23]
	s_waitcnt vmcnt(3)
; #define MFMA(a, b, c) __builtin_amdgcn_mfma_f32_32x32x16_bf16((a), (b), (c), 0, 0, 0)
; template <int DK, int MODE> ...
;     ...
; #pragma unroll
;       for (int ks = 0; ks < NKS; ++ks) { kf0[ks] = *(const bf16x8*)(kb + ks * 16); kf1[ks] = *(const bf16x8*)(kb + 32 * LDK + ks * 16); }
;       if (MODE == 1) {
;         const float* fb = sF + cur * 64 + 4 * h;
; #pragma unroll
;         for (int g = 0; g < 4; ++g) {
;           const f32x4 f0 = *(const f32x4*)(fb + 8 * g), f1 = *(const f32x4*)(fb + 32 + 8 * g);
;           s0[4 * g] = f0.x; s0[4 * g + 1] = f0.y; s0[4 * g + 2] = f0.z; s0[4 * g + 3] = f0.w;
;           s1[4 * g] = f1.x; s1[4 * g + 1] = f1.y; s1[4 * g + 2] = f1.z; s1[4 * g + 3] = f1.w;
;         }
;       } else {
; #pragma unroll
;         for (int e = 0; e < 16; ++e) { s0[e] = 0.f; s1[e] = 0.f; }
;       }
;       __builtin_amdgcn_iglp_opt(0);
;       __builtin_amdgcn_s_setprio(1);
; #pragma unroll
;       for (int ks = 0; ks < NKS; ++ks) { s0 = MFMA(kf0[ks], qf[ks], s0); s1 = MFMA(kf1[ks], qf[ks], s1); }
;       __builtin_amdgcn_s_setprio(0);
;       const bf16_t* vb = sV + cur * 64 * 72 + l32 * 72 + h * 8;
;       bf16x8 vf0[4], vf1[4];
; #pragma unroll
;       for (int j = 0; j < 4; ++j) { vf0[j] = *(const bf16x8*)(vb + j * 16); vf1[j] = *(const bf16x8*)(vb + 32 * 72 + j * 16); }
;       __builtin_amdgcn_sched_barrier(0);
;       const bool need_mask = CAUSAL && (key0 + 63 >= tq0);
;       bf16x8 pf[4];
;       if (MODE != 2) {
;         if (need_mask) {
; #pragma unroll
;           for (int e = 0; e < 16; ++e) {
;             const int key = key0 + 8 * (e >> 2) + 4 * h + (e & 3);
;             if (key > qpos) s0[e] = -1e30f;
;             if (key + 32 > qpos) s1[e] = -1e30f;
;           }
;         }
;         float mx = s0[0];
; #pragma unroll
;         for (int e = 1; e < 16; ++e) mx = fmaxf(mx, s0[e]);
; #pragma unroll
;         for (int e = 0; e < 16; ++e) mx = fmaxf(mx, s1[e]);
;         mx = fmaxf(mx, __shfl_xor(mx, 32));
;         if (__any(mx > m + 8.f)) {
;           const float mnew = fmaxf(m, mx);
;           const float alpha = __builtin_amdgcn_exp2f(m - mnew);
;           m = mnew; lsum *= alpha;
; #pragma unroll
;           for (int e = 0; e < 16; ++e) { o0[e] *= alpha; o1[e] *= alpha; }
;         }
;         float ps0 = 0.f, ps1 = 0.f, ps2 = 0.f, ps3 = 0.f;
; #pragma unroll
;         for (int e = 0; e < 16; e += 4) {
	ds_write_b128 v151, v[2:5]
	v_mul_lo_u32 v2, v24, s54
	v_lshl_add_u32 v152, v38, 4, v2
	v_lshl_add_u64 v[2:3], s[22:23], 0, v[14:15]
	s_waitcnt vmcnt(2)
	ds_write_b128 v152, v[6:9]
	v_mul_u32_u24_e32 v6, 0x48, v36
	v_and_b32_e32 v7, 64, v192
	v_lshl_add_u32 v0, v6, 1, v0
	v_xor_b32_e32 v6, 32, v192
	v_add_u32_e32 v7, 64, v7
	v_cmp_lt_i32_e32 vcc, v6, v7
	v_lshl_add_u64 v[140:141], v[2:3], 0, v[10:11]
	v_lshl_add_u64 v[4:5], s[22:23], 0, v[16:17]
	v_cndmask_b32_e32 v6, v192, v6, vcc
	v_add_co_u32_e32 v2, vcc, s2, v140
	v_lshl_add_u64 v[142:143], v[4:5], 0, v[12:13]
	s_nop 0
	v_addc_co_u32_e32 v3, vcc, 0, v141, vcc
	s_waitcnt vmcnt(1)
	ds_write_b128 v132, v[26:29] offset:18432
	s_waitcnt vmcnt(0)
	ds_write_b128 v134, v[30:33] offset:18432
	s_waitcnt lgkmcnt(0)
	s_barrier
	global_load_dwordx4 v[50:53], v[2:3], off
	v_add_co_u32_e32 v2, vcc, s2, v142
	global_load_dwordx4 v[58:61], v[136:137], off offset:128
	s_nop 0
	v_addc_co_u32_e32 v3, vcc, 0, v143, vcc
	global_load_dwordx4 v[54:57], v[2:3], off
	global_load_dwordx4 v[62:65], v[138:139], off offset:128
	ds_read_b128 v[2:5], v0 offset:4608
	ds_read_b128 v[18:21], v0
	ds_read_b128 v[34:37], v0 offset:32
	ds_read_b128 v[22:25], v0 offset:4640
	ds_read_b128 v[38:41], v0 offset:64
	ds_read_b128 v[26:29], v0 offset:4672
	ds_read_b128 v[42:45], v0 offset:96
	ds_read_b128 v[30:33], v0 offset:4704
	v_lshlrev_b32_e32 v133, 2, v6
	s_setprio 1
	s_waitcnt lgkmcnt(7)
	v_mfma_f32_32x32x16_bf16 v[2:17], v[2:5], v[78:81], 0
	s_waitcnt lgkmcnt(4)
	v_mfma_f32_32x32x16_bf16 v[2:17], v[22:25], v[74:77], v[2:17]
	s_waitcnt lgkmcnt(2)
	v_mfma_f32_32x32x16_bf16 v[2:17], v[26:29], v[70:73], v[2:17]
	s_waitcnt lgkmcnt(0)
	v_mfma_f32_32x32x16_bf16 v[2:17], v[30:33], v[66:69], v[2:17]
	s_setprio 0
	v_mfma_f32_32x32x16_bf16 v[18:33], v[18:21], v[78:81], 0
	ds_read_b128 v[82:85], v0 offset:18432
	ds_read_b128 v[86:89], v0 offset:18464
	ds_read_b128 v[90:93], v0 offset:23040
	ds_read_b128 v[94:97], v0 offset:23072
	ds_read_b128 v[98:101], v0 offset:18496
	ds_read_b128 v[102:105], v0 offset:18528
	ds_read_b128 v[106:109], v0 offset:23104
	v_mfma_f32_32x32x16_bf16 v[18:33], v[34:37], v[74:77], v[18:33]
	ds_read_b128 v[110:113], v0 offset:23136
	v_mfma_f32_32x32x16_bf16 v[18:33], v[38:41], v[70:73], v[18:33]
	v_mfma_f32_32x32x16_bf16 v[18:33], v[42:45], v[66:69], v[18:33]
	s_nop 11
	v_max_f32_e32 v34, v19, v19
	v_max_f32_e32 v35, v18, v18
	v_max_f32_e32 v34, v35, v34
	v_max3_f32 v34, v34, v20, v21
	v_max3_f32 v34, v34, v22, v23
	v_max3_f32 v34, v34, v24, v25
	v_max3_f32 v34, v34, v26, v27
	v_max3_f32 v34, v34, v28, v29
	v_max3_f32 v34, v34, v30, v31
	v_max3_f32 v34, v34, v32, v33
	v_max3_f32 v34, v34, v2, v3
	v_max3_f32 v34, v34, v4, v5
	v_max3_f32 v34, v34, v6, v7
	v_max3_f32 v34, v34, v8, v9
	v_max3_f32 v34, v34, v10, v11
	v_max3_f32 v34, v34, v12, v13
	v_max3_f32 v34, v34, v14, v15
	v_max3_f32 v34, v34, v16, v17
	ds_bpermute_b32 v35, v133, v34
	s_mov_b32 s2, 0xf149f2ca
	s_waitcnt lgkmcnt(0)
	v_max_f32_e32 v35, v35, v35
	v_max_f32_e32 v34, v34, v35
	v_cmp_lt_f32_e32 vcc, s2, v34
	s_cmp_eq_u64 vcc, 0
	v_max_f32_e32 v114, 0xf149f2ca, v34
	s_cselect_b64 vcc, -1, 0
	v_cndmask_b32_e32 v135, v114, v198, vcc
	v_sub_f32_e32 v19, v19, v135
	v_sub_f32_e32 v35, 0xf149f2ca, v114
	v_sub_f32_e32 v18, v18, v135
	v_exp_f32_e32 v114, v19
	v_sub_f32_e32 v19, v20, v135
	v_sub_f32_e32 v20, v21, v135
	v_sub_f32_e32 v21, v23, v135
	v_exp_f32_e32 v18, v18
	v_exp_f32_e32 v19, v19
	v_exp_f32_e32 v115, v20
	v_sub_f32_e32 v20, v22, v135
	v_exp_f32_e32 v22, v21
	v_sub_f32_e32 v21, v24, v135
	v_sub_f32_e32 v23, v25, v135
	v_sub_f32_e32 v25, v27, v135
	v_exp_f32_e32 v20, v20
	v_exp_f32_e32 v21, v21
	v_exp_f32_e32 v23, v23
	v_sub_f32_e32 v24, v26, v135
	v_exp_f32_e32 v26, v25
	v_sub_f32_e32 v25, v28, v135
	v_sub_f32_e32 v27, v29, v135
	v_sub_f32_e32 v29, v31, v135
	v_exp_f32_e32 v24, v24
	v_exp_f32_e32 v25, v25
	v_exp_f32_e32 v27, v27
	v_sub_f32_e32 v28, v30, v135
	v_exp_f32_e32 v30, v29
	v_sub_f32_e32 v29, v32, v135
	v_sub_f32_e32 v31, v33, v135
	v_sub_f32_e32 v3, v3, v135
	v_exp_f32_e32 v28, v28
	v_exp_f32_e32 v29, v29
	v_exp_f32_e32 v31, v31
	v_sub_f32_e32 v2, v2, v135
	v_exp_f32_e32 v32, v3
	v_sub_f32_e32 v3, v4, v135
	v_sub_f32_e32 v4, v5, v135
	v_sub_f32_e32 v5, v7, v135
	v_sub_f32_e32 v7, v9, v135
	v_sub_f32_e32 v9, v11, v135
	v_sub_f32_e32 v11, v13, v135
	v_sub_f32_e32 v13, v15, v135
	v_exp_f32_e32 v2, v2
	v_exp_f32_e32 v3, v3
	v_exp_f32_e32 v33, v4
	v_sub_f32_e32 v4, v6, v135
	v_exp_f32_e32 v6, v5
	v_sub_f32_e32 v5, v8, v135
	v_sub_f32_e32 v8, v10, v135
	v_exp_f32_e32 v10, v9
	v_sub_f32_e32 v9, v12, v135
	v_sub_f32_e32 v12, v14, v135
	v_exp_f32_e32 v14, v13
	v_sub_f32_e32 v13, v16, v135
	v_sub_f32_e32 v15, v17, v135
	v_pk_add_f32 v[16:17], v[18:19], 0 op_sel_hi:[1,0]
	v_pk_add_f32 v[116:117], v[114:115], 0 op_sel_hi:[1,0]
	v_exp_f32_e32 v4, v4
	v_exp_f32_e32 v5, v5
	v_exp_f32_e32 v7, v7
	v_pk_add_f32 v[16:17], v[20:21], v[16:17]
	v_pk_add_f32 v[116:117], v[22:23], v[116:117]
	v_exp_f32_e32 v8, v8
	v_exp_f32_e32 v9, v9
	v_exp_f32_e32 v11, v11
	v_pk_add_f32 v[16:17], v[24:25], v[16:17]
	v_pk_add_f32 v[116:117], v[26:27], v[116:117]
	v_exp_f32_e32 v35, v35
	v_exp_f32_e32 v12, v12
	v_exp_f32_e32 v13, v13
	v_exp_f32_e32 v15, v15
	v_pk_add_f32 v[16:17], v[28:29], v[16:17]
	v_pk_add_f32 v[154:155], v[30:31], v[116:117]
	v_cvt_pk_bf16_f32 v118, v2, v32
	v_cvt_pk_bf16_f32 v119, v3, v33
	v_pk_add_f32 v[2:3], v[2:3], v[16:17]
	v_pk_add_f32 v[16:17], v[32:33], v[154:155]
	v_cvt_pk_bf16_f32 v120, v4, v6
	v_cvt_pk_bf16_f32 v121, v5, v7
	v_pk_add_f32 v[2:3], v[4:5], v[2:3]
	v_pk_add_f32 v[4:5], v[6:7], v[16:17]
	v_pk_add_f32 v[2:3], v[8:9], v[2:3]
; #define MFMA(a, b, c) __builtin_amdgcn_mfma_f32_32x32x16_bf16((a), (b), (c), 0, 0, 0)
; DI unsigned pack2(float a, float b) { f32x2 v = {a, b}; return __builtin_bit_cast(unsigned, __builtin_convertvector(v, bf16v2)); }
; template <int DK, int MODE> ...
;     ...
;         if (__any(mx > m + 8.f)) {
;           const float mnew = fmaxf(m, mx);
;           const float alpha = __builtin_amdgcn_exp2f(m - mnew);
;           m = mnew; lsum *= alpha;
; #pragma unroll
;           for (int e = 0; e < 16; ++e) { o0[e] *= alpha; o1[e] *= alpha; }
;         }
;         float ps0 = 0.f, ps1 = 0.f, ps2 = 0.f, ps3 = 0.f;
; #pragma unroll
;         for (int e = 0; e < 16; e += 4) {
;           s0[e] = __builtin_amdgcn_exp2f(s0[e] - m); s0[e + 1] = __builtin_amdgcn_exp2f(s0[e + 1] - m); s0[e + 2] = __builtin_amdgcn_exp2f(s0[e + 2] - m); s0[e + 3] = __builtin_amdgcn_exp2f(s0[e + 3] - m);
;           ps0 += s0[e]; ps1 += s0[e + 1]; ps2 += s0[e + 2]; ps3 += s0[e + 3];
;         }
; #pragma unroll
;         for (int e = 0; e < 16; e += 4) {
;           s1[e] = __builtin_amdgcn_exp2f(s1[e] - m); s1[e + 1] = __builtin_amdgcn_exp2f(s1[e + 1] - m); s1[e + 2] = __builtin_amdgcn_exp2f(s1[e + 2] - m); s1[e + 3] = __builtin_amdgcn_exp2f(s1[e + 3] - m);
;           ps0 += s1[e]; ps1 += s1[e + 1]; ps2 += s1[e + 2]; ps3 += s1[e + 3];
;         }
;         lsum += (ps0 + ps1) + (ps2 + ps3);
;     ...
; #pragma unroll
;       for (int j = 0; j < 2; ++j) {
;         u32x4 a, b;
;         a.x = pack2(s0[8 * j], s0[8 * j + 1]); a.y = pack2(s0[8 * j + 2], s0[8 * j + 3]); a.z = pack2(s0[8 * j + 4], s0[8 * j + 5]); a.w = pack2(s0[8 * j + 6], s0[8 * j + 7]);
;         b.x = pack2(s1[8 * j], s1[8 * j + 1]); b.y = pack2(s1[8 * j + 2], s1[8 * j + 3]); b.z = pack2(s1[8 * j + 4], s1[8 * j + 5]); b.w = pack2(s1[8 * j + 6], s1[8 * j + 7]);
;         pf[j] = __builtin_bit_cast(bf16x8, a); pf[2 + j] = __builtin_bit_cast(bf16x8, b);
;       }
;       __builtin_amdgcn_s_setprio(1);
; #pragma unroll
;       for (int j = 0; j < 4; ++j) { o0 = MFMA(vf0[j], pf[j], o0); o1 = MFMA(vf1[j], pf[j], o1); }
;       __builtin_amdgcn_s_setprio(0);
;     }
;     __builtin_amdgcn_sched_barrier(0);
;     if (more) swrite(cur ^ 1);
;     if (MODE == 2) { const int done = __all(R == 0.f); if (lane == 0) sFlag[cur * 4 + wave] = done; }
;     __syncthreads();
	v_pk_add_f32 v[4:5], v[10:11], v[4:5]
	v_mul_f32_e32 v34, 0, v35
	v_pk_add_f32 v[2:3], v[12:13], v[2:3]
	v_pk_add_f32 v[4:5], v[14:15], v[4:5]
	v_cndmask_b32_e64 v34, v34, 0, vcc
	v_pk_add_f32 v[2:3], v[2:3], v[4:5]
	v_mov_b32_e32 v35, v34
	v_mov_b32_e32 v36, v34
	v_mov_b32_e32 v37, v34
	v_mov_b32_e32 v38, v34
	v_mov_b32_e32 v39, v34
	v_mov_b32_e32 v40, v34
	v_mov_b32_e32 v41, v34
	v_mov_b32_e32 v42, v34
	v_mov_b32_e32 v43, v34
	v_mov_b32_e32 v44, v34
	v_mov_b32_e32 v45, v34
	v_mov_b32_e32 v46, v34
	v_mov_b32_e32 v47, v34
	v_mov_b32_e32 v48, v34
	v_mov_b32_e32 v49, v34
	v_cvt_pk_bf16_f32 v114, v18, v114
	v_cvt_pk_bf16_f32 v115, v19, v115
	v_cvt_pk_bf16_f32 v116, v20, v22
	v_cvt_pk_bf16_f32 v117, v21, v23
	v_cvt_pk_bf16_f32 v122, v24, v26
	v_cvt_pk_bf16_f32 v123, v25, v27
	v_cvt_pk_bf16_f32 v124, v28, v30
	v_cvt_pk_bf16_f32 v125, v29, v31
	v_cvt_pk_bf16_f32 v126, v8, v10
	v_cvt_pk_bf16_f32 v127, v9, v11
	v_cvt_pk_bf16_f32 v128, v12, v14
	v_cvt_pk_bf16_f32 v129, v13, v15
	v_add_f32_e32 v153, v2, v3
	s_setprio 1
	v_mov_b64_e32 v[2:3], v[34:35]
	v_mov_b64_e32 v[4:5], v[36:37]
	v_mov_b64_e32 v[6:7], v[38:39]
	v_mov_b64_e32 v[8:9], v[40:41]
	v_mov_b64_e32 v[10:11], v[42:43]
	v_mov_b64_e32 v[12:13], v[44:45]
	v_mov_b64_e32 v[14:15], v[46:47]
	v_mov_b64_e32 v[16:17], v[48:49]
	v_mfma_f32_32x32x16_bf16 v[18:33], v[82:85], v[114:117], v[34:49]
	v_add_f32_e32 v154, v34, v153
	v_mfma_f32_32x32x16_bf16 v[2:17], v[90:93], v[114:117], v[2:17]
	v_mfma_f32_32x32x16_bf16 v[18:33], v[86:89], v[122:125], v[18:33]
	v_mfma_f32_32x32x16_bf16 v[2:17], v[94:97], v[122:125], v[2:17]
	v_mfma_f32_32x32x16_bf16 v[18:33], v[98:101], v[118:121], v[18:33]
	v_mfma_f32_32x32x16_bf16 v[2:17], v[106:109], v[118:121], v[2:17]
	v_mfma_f32_32x32x16_bf16 v[18:33], v[102:105], v[126:129], v[18:33]
	v_mfma_f32_32x32x16_bf16 v[2:17], v[110:113], v[126:129], v[2:17]
	s_setprio 0
	s_movk_i32 s2, 0x4000
	v_add_co_u32_e32 v34, vcc, s2, v140
	s_waitcnt vmcnt(3)
	ds_write_b128 v151, v[50:53] offset:9216
	v_addc_co_u32_e32 v35, vcc, 0, v141, vcc
	s_waitcnt vmcnt(1)
	ds_write_b128 v152, v[54:57] offset:9216
	ds_write_b128 v132, v[58:61] offset:27648
	s_waitcnt vmcnt(0)
	ds_write_b128 v134, v[62:65] offset:27648
	s_waitcnt lgkmcnt(0)
	s_barrier
	global_load_dwordx4 v[82:85], v[34:35], off
	v_add_co_u32_e32 v34, vcc, s2, v142
	global_load_dwordx4 v[90:93], v[136:137], off offset:256
	s_nop 0
	v_addc_co_u32_e32 v35, vcc, 0, v143, vcc
	global_load_dwordx4 v[86:89], v[34:35], off
	global_load_dwordx4 v[94:97], v[138:139], off offset:256
	ds_read_b128 v[34:37], v0 offset:13824
	ds_read_b128 v[50:53], v0 offset:9216
	ds_read_b128 v[98:101], v0 offset:9248
	ds_read_b128 v[54:57], v0 offset:13856
	ds_read_b128 v[102:105], v0 offset:9280
	ds_read_b128 v[58:61], v0 offset:13888
	ds_read_b128 v[62:65], v0 offset:13920
	ds_read_b128 v[156:159], v0 offset:9312
	s_setprio 1
	s_waitcnt lgkmcnt(7)
	v_mfma_f32_32x32x16_bf16 v[34:49], v[34:37], v[78:81], 0
	s_waitcnt lgkmcnt(4)
	v_mfma_f32_32x32x16_bf16 v[34:49], v[54:57], v[74:77], v[34:49]
	s_waitcnt lgkmcnt(2)
	v_mfma_f32_32x32x16_bf16 v[34:49], v[58:61], v[70:73], v[34:49]
	s_waitcnt lgkmcnt(1)
	v_mfma_f32_32x32x16_bf16 v[34:49], v[62:65], v[66:69], v[34:49]
	s_setprio 0
	v_mfma_f32_32x32x16_bf16 v[50:65], v[50:53], v[78:81], 0
	ds_read_b128 v[122:125], v0 offset:27648
	ds_read_b128 v[114:117], v0 offset:27680
	ds_read_b128 v[126:129], v0 offset:32256
	ds_read_b128 v[118:121], v0 offset:32288
	ds_read_b128 v[106:109], v0 offset:27712
	ds_read_b128 v[110:113], v0 offset:32320
	v_mfma_f32_32x32x16_bf16 v[50:65], v[98:101], v[74:77], v[50:65]
	ds_read_b128 v[98:101], v0 offset:32352
	v_mfma_f32_32x32x16_bf16 v[50:65], v[102:105], v[70:73], v[50:65]
	ds_read_b128 v[102:105], v0 offset:27744
	s_waitcnt lgkmcnt(8)
	v_mfma_f32_32x32x16_bf16 v[50:65], v[156:159], v[66:69], v[50:65]
	s_nop 11
	v_max_f32_e32 v153, v51, v51
	v_max_f32_e32 v155, v50, v50
	v_max_f32_e32 v153, v155, v153
	v_max3_f32 v153, v153, v52, v53
	v_max3_f32 v153, v153, v54, v55
	v_max3_f32 v153, v153, v56, v57
	v_max3_f32 v153, v153, v58, v59
	v_max3_f32 v153, v153, v60, v61
	v_max3_f32 v153, v153, v62, v63
	v_max3_f32 v153, v153, v64, v65
	v_max3_f32 v153, v153, v34, v35
	v_max3_f32 v153, v153, v36, v37
	v_max3_f32 v153, v153, v38, v39
	v_max3_f32 v153, v153, v40, v41
	v_max3_f32 v153, v153, v42, v43
	v_max3_f32 v153, v153, v44, v45
	v_max3_f32 v153, v153, v46, v47
	v_max3_f32 v153, v153, v48, v49
	ds_bpermute_b32 v155, v133, v153
	s_waitcnt lgkmcnt(0)
	v_max_f32_e32 v155, v155, v155
	v_max_f32_e32 v155, v153, v155
	v_add_f32_e32 v153, 0x41000000, v135
	v_cmp_gt_f32_e32 vcc, v155, v153
	s_cbranch_vccz .LBB0_590
	v_max_f32_e32 v153, v155, v155
	v_max_f32_e32 v155, v135, v135
	v_max_f32_e32 v155, v155, v153
	v_sub_f32_e32 v135, v135, v155
	v_exp_f32_e32 v156, v135
	v_add_f32_e32 v153, 0x41000000, v155
	v_mov_b32_e32 v135, v155
	v_pk_mul_f32 v[32:33], v[32:33], v[156:157] op_sel_hi:[1,0]
	v_pk_mul_f32 v[30:31], v[30:31], v[156:157] op_sel_hi:[1,0]
	v_pk_mul_f32 v[28:29], v[28:29], v[156:157] op_sel_hi:[1,0]
	v_pk_mul_f32 v[26:27], v[26:27], v[156:157] op_sel_hi:[1,0]
	v_pk_mul_f32 v[24:25], v[24:25], v[156:157] op_sel_hi:[1,0]
	v_pk_mul_f32 v[22:23], v[22:23], v[156:157] op_sel_hi:[1,0]
	v_pk_mul_f32 v[20:21], v[20:21], v[156:157] op_sel_hi:[1,0]
	v_pk_mul_f32 v[18:19], v[18:19], v[156:157] op_sel_hi:[1,0]
	v_pk_mul_f32 v[16:17], v[16:17], v[156:157] op_sel_hi:[1,0]
	v_pk_mul_f32 v[14:15], v[14:15], v[156:157] op_sel_hi:[1,0]
	v_pk_mul_f32 v[12:13], v[12:13], v[156:157] op_sel_hi:[1,0]
	v_pk_mul_f32 v[10:11], v[10:11], v[156:157] op_sel_hi:[1,0]
	v_pk_mul_f32 v[8:9], v[8:9], v[156:157] op_sel_hi:[1,0]
	v_pk_mul_f32 v[6:7], v[6:7], v[156:157] op_sel_hi:[1,0]
	v_pk_mul_f32 v[4:5], v[4:5], v[156:157] op_sel_hi:[1,0]
	v_pk_mul_f32 v[2:3], v[2:3], v[156:157] op_sel_hi:[1,0]
	v_mul_f32_e32 v154, v154, v156

; __global__ void __launch_bounds__(256, 2) mega(Params p_unused) {
;   __shared__ __attribute__((aligned(16))) char smem[SMEM_BYTES];
	.amdhsa_kernel _Z4mega6Params
		.amdhsa_group_segment_fixed_size 74752
		.amdhsa_private_segment_fixed_size 0
		.amdhsa_kernarg_size 648
		.amdhsa_user_sgpr_count 2
		.amdhsa_user_sgpr_dispatch_ptr 0
		.amdhsa_user_sgpr_queue_ptr 0
		.amdhsa_user_sgpr_kernarg_segment_ptr 1
		.amdhsa_user_sgpr_dispatch_id 0
		.amdhsa_user_sgpr_kernarg_preload_length 0
		.amdhsa_user_sgpr_kernarg_preload_offset 0
		.amdhsa_user_sgpr_private_segment_size 0
		.amdhsa_uses_dynamic_stack 0
		.amdhsa_enable_private_segment 0
		.amdhsa_system_sgpr_workgroup_id_x 1
		.amdhsa_system_sgpr_workgroup_id_y 0
		.amdhsa_system_sgpr_workgroup_id_z 0
		.amdhsa_system_sgpr_workgroup_info 0
		.amdhsa_system_vgpr_workitem_id 2
		.amdhsa_next_free_vgpr 240
		.amdhsa_next_free_sgpr 102
		.amdhsa_accum_offset 240
		.amdhsa_reserve_vcc 1
		.amdhsa_float_round_mode_32 0
		.amdhsa_float_round_mode_16_64 0
		.amdhsa_float_denorm_mode_32 3
		.amdhsa_float_denorm_mode_16_64 3
		.amdhsa_dx10_clamp 1
		.amdhsa_ieee_mode 1
		.amdhsa_fp16_overflow 0
		.amdhsa_tg_split 0
		.amdhsa_exception_fp_ieee_invalid_op 0
		.amdhsa_exception_fp_denorm_src 0
		.amdhsa_exception_fp_ieee_div_zero 0
		.amdhsa_exception_fp_ieee_overflow 0
		.amdhsa_exception_fp_ieee_underflow 0
		.amdhsa_exception_fp_ieee_inexact 0
		.amdhsa_exception_int_div_zero 0
	.end_amdhsa_kernel

; __global__ void __launch_bounds__(256, 2) mega(Params p_unused) {
;   __shared__ __attribute__((aligned(16))) char smem[SMEM_BYTES];
amdhsa.kernels:
  - .agpr_count:     0
    .args:
      - .offset:         0
        .size:           392
        .value_kind:     by_value
      - .offset:         392
        .size:           4
        .value_kind:     hidden_block_count_x
      - .offset:         396
        .size:           4
        .value_kind:     hidden_block_count_y
      - .offset:         400
        .size:           4
        .value_kind:     hidden_block_count_z
      - .offset:         404
        .size:           2
        .value_kind:     hidden_group_size_x
      - .offset:         406
        .size:           2
        .value_kind:     hidden_group_size_y
      - .offset:         408
        .size:           2
        .value_kind:     hidden_group_size_z
      - .offset:         410
        .size:           2
        .value_kind:     hidden_remainder_x
      - .offset:         412
        .size:           2
        .value_kind:     hidden_remainder_y
      - .offset:         414
        .size:           2
        .value_kind:     hidden_remainder_z
      - .offset:         432
        .size:           8
        .value_kind:     hidden_global_offset_x
      - .offset:         440
        .size:           8
        .value_kind:     hidden_global_offset_y
      - .offset:         448
        .size:           8
        .value_kind:     hidden_global_offset_z
      - .offset:         456
        .size:           2
        .value_kind:     hidden_grid_dims
      - .offset:         480
        .size:           8
        .value_kind:     hidden_multigrid_sync_arg
    .group_segment_fixed_size: 74752
    .kernarg_segment_align: 8
    .kernarg_segment_size: 648
    .language:       OpenCL C
    .language_version:
      - 2
      - 0
    .max_flat_workgroup_size: 256
    .name:           _Z4mega6Params
    .private_segment_fixed_size: 0
    .sgpr_count:     108
    .sgpr_spill_count: 74
    .symbol:         _Z4mega6Params.kd
    .uniform_work_group_size: 1
    .uses_dynamic_stack: false
    .vgpr_count:     240
    .vgpr_spill_count: 0
    .wavefront_size: 64
